# FFT stage-2 results staged through LDS and stored as whole 256-B row segments
# baseline (speedup 1.0000x reference)
; __device__ void fft2_phase(int wv, const Params& p, unsigned char* lds) {
;     const int tid = otid(wv), lane = tid & 63, w = __builtin_amdgcn_readfirstlane(tid >> 6), lr = lane & 15, lq = lane >> 4;
;     constexpr int PW = 136;
;     const bf16_t* A1 = (const bf16_t*)(p.ws + WS_BIG2); bf16_t* Y = (bf16_t*)(p.ws + WS_BIG1);
;     const bf16_t* ctg = (const bf16_t*)(p.ws + WS_TAB + TAB_CT128); const bf16_t* stg = (const bf16_t*)(p.ws + WS_TAB + TAB_ST128);
;     bf16_t* CT = (bf16_t*)lds; bf16_t* ST = CT + 128 * PW; bf16_t* XR = ST + 128 * PW; bf16_t* XI = XR + 128 * PW;
;     for (int idx = tid; idx < 128 * 16; idx += NTHR) { const int r = idx >> 4, c8 = (idx & 15) * 8;
;         *(bf16x8*)(CT + r * PW + c8) = *(const bf16x8*)(ctg + r * 128 + c8); *(bf16x8*)(ST + r * PW + c8) = *(const bf16x8*)(stg + r * 128 + c8); }
;     __syncthreads();
;     for (int unit = blockIdx.x; unit < 2048; unit += gridDim.x) {
;         const int gi = unit >> 3, cb = unit & 7;
;         const int seq = gi < 64 ? 0 : (gi < 128 ? 1 : 2); const int ka = gi - (seq == 0 ? 0 : (seq == 1 ? 64 : 128)); const int N1 = seq == 2 ? 128 : 64;
;         const size_t sbase = (size_t)seq * 8192;
; #pragma unroll
;         for (int ps = 0; ps < 4; ++ps) { const int idx = tid + ps * NTHR, b = idx & 127, c8 = (idx >> 7) * 8;
;             const bf16_t* rp = A1 + ((size_t)gi * 128 + b) * 2048 + cb * 128 + c8; const bf16x8 vr = *(const bf16x8*)rp, vi = *(const bf16x8*)(rp + 1024);
; #pragma unroll
;             for (int e = 0; e < 8; ++e) { XR[(c8 + e) * PW + b] = (bf16_t)vr[e]; XI[(c8 + e) * PW + b] = (bf16_t)vi[e]; } }
;         __syncthreads();
;         bf16x8 xr[4], xi[4], nxr[4];
; #pragma unroll
;         for (int kk = 0; kk < 4; ++kk) { xr[kk] = *(const bf16x8*)(XR + (16 * w + lr) * PW + 32 * kk + 8 * lq); xi[kk] = *(const bf16x8*)(XI + (16 * w + lr) * PW + 32 * kk + 8 * lq);
;             union { bf16x8 v; unsigned u[4]; } t; t.v = xr[kk]; t.u[0] ^= 0x80008000u; t.u[1] ^= 0x80008000u; t.u[2] ^= 0x80008000u; t.u[3] ^= 0x80008000u; nxr[kk] = t.v; }
; #pragma unroll
;         for (int i = 0; i < 8; ++i) { f32x4 re = {0, 0, 0, 0}, im = {0, 0, 0, 0};
; #pragma unroll
;             for (int kk = 0; kk < 4; ++kk) { const bf16x8 cf = *(const bf16x8*)(CT + (16 * i + lr) * PW + 32 * kk + 8 * lq), sf = *(const bf16x8*)(ST + (16 * i + lr) * PW + 32 * kk + 8 * lq);
.LBB0_388:
	s_or_b64 exec, exec, s[0:1]
	v_readlane_b32 s0, v254, 9
	v_readlane_b32 s1, v254, 10
	s_andn2_b64 vcc, exec, s[0:1]
	s_waitcnt lgkmcnt(0)
	s_barrier
	s_cbranch_vccnz .LBB0_391
	v_and_b32_e32 v3, 0x7f, v2
	v_readlane_b32 s0, v254, 13
	v_lshlrev_b32_e32 v4, 12, v3
	v_mov_b32_e32 v5, v0
	v_readlane_b32 s1, v254, 14
	v_bfe_u32 v1, v2, 4, 2
	v_lshlrev_b32_e32 v6, 4, v1
	v_lshl_add_u64 v[52:53], s[0:1], 0, v[4:5]
	s_ashr_i32 s1, s10, 2
	s_and_b32 s0, s1, -16
	v_bfi_b32 v4, -16, s1, v2
	s_movk_i32 s1, 0x110
	v_mul_lo_u32 v5, v4, s1
	s_ashr_i32 s1, s0, 31
	s_lshl_b64 s[0:1], s[0:1], 1
	v_readlane_b32 s6, v254, 57
	v_readlane_b32 s7, v254, 59
	s_add_u32 s0, s76, s0
	v_lshlrev_b32_e32 v4, 3, v1
	v_add3_u32 v1, s6, v5, v6
	v_add3_u32 v80, s7, v5, v6
	s_addc_u32 s1, s77, s1
	v_mov_b32_e32 v5, v0
	v_lshl_add_u64 v[54:55], s[0:1], 0, v[4:5]
	v_ashrrev_i32_e32 v4, 4, v2
	v_and_b32_e32 v56, -8, v4
	s_movk_i32 s0, 0x88
	v_mul_lo_u32 v5, v56, s0
	v_add_lshl_u32 v5, v5, v3, 1
	v_or_b32_e32 v4, 7, v4
	v_add_u32_e32 v7, 0x110, v5
	v_mul_lo_u32 v4, v4, s0
	v_add_u32_e32 v83, s6, v7
	v_add_u32_e32 v84, s7, v7
	v_add_u32_e32 v7, 0x220, v5
	v_add_lshl_u32 v4, v4, v3, 1
	v_add_u32_e32 v85, s6, v7
	v_add_u32_e32 v86, s7, v7
	v_add_u32_e32 v7, 0x330, v5
	v_add_u32_e32 v95, s6, v4
	v_add_u32_e32 v96, s7, v4
	v_add_u32_e32 v4, 0x200, v2
	v_add_u32_e32 v87, s6, v7
	v_add_u32_e32 v88, s7, v7
	v_add_u32_e32 v7, 0x440, v5
	v_ashrrev_i32_e32 v4, 4, v4
	v_add_u32_e32 v81, s6, v5
	v_add_u32_e32 v82, s7, v5
	v_add_u32_e32 v89, s6, v7
	v_add_u32_e32 v90, s7, v7
	v_add_u32_e32 v7, 0x550, v5
	v_add_u32_e32 v5, 0x660, v5
	v_and_b32_e32 v58, -8, v4
	v_add_u32_e32 v93, s6, v5
	v_add_u32_e32 v94, s7, v5
	v_mul_lo_u32 v5, v58, s0
	v_add_lshl_u32 v5, v5, v3, 1
	v_or_b32_e32 v4, 7, v4
	v_add_u32_e32 v91, s6, v7
	v_add_u32_e32 v92, s7, v7
	v_add_u32_e32 v7, 0x110, v5
	v_mul_lo_u32 v4, v4, s0
	v_add_u32_e32 v99, s6, v7
	v_add_u32_e32 v100, s7, v7
	v_add_u32_e32 v7, 0x220, v5
	v_add_lshl_u32 v4, v4, v3, 1
	v_add_u32_e32 v101, s6, v7
	v_add_u32_e32 v102, s7, v7
	v_add_u32_e32 v7, 0x330, v5
	v_add_u32_e32 v111, s6, v4
	v_add_u32_e32 v112, s7, v4
	v_add_u32_e32 v4, 0x400, v2
	v_add_u32_e32 v103, s6, v7
	v_add_u32_e32 v104, s7, v7
	v_add_u32_e32 v7, 0x440, v5
	v_ashrrev_i32_e32 v4, 4, v4
	v_add_u32_e32 v97, s6, v5
	v_add_u32_e32 v98, s7, v5
	v_add_u32_e32 v105, s6, v7
	v_add_u32_e32 v106, s7, v7
	v_add_u32_e32 v7, 0x550, v5
	v_add_u32_e32 v5, 0x660, v5
	v_and_b32_e32 v60, -8, v4
	v_add_u32_e32 v109, s6, v5
	v_add_u32_e32 v110, s7, v5
	v_mul_lo_u32 v5, v60, s0
	v_add_lshl_u32 v5, v5, v3, 1
	v_and_b32_e32 v50, 15, v2
	v_add_u32_e32 v107, s6, v7
	v_add_u32_e32 v108, s7, v7
	v_add_u32_e32 v7, 0x110, v5
	v_or_b32_e32 v4, 7, v4
	v_add_u32_e32 v2, 0x600, v2
	v_add_u32_e32 v115, s6, v7
	v_add_u32_e32 v116, s7, v7
	v_add_u32_e32 v7, 0x220, v5
	v_mul_lo_u32 v4, v4, s0
	v_ashrrev_i32_e32 v2, 4, v2
	v_add_u32_e32 v117, s6, v7
	v_add_u32_e32 v118, s7, v7
	v_add_u32_e32 v7, 0x330, v5
	v_add_lshl_u32 v4, v4, v3, 1
	v_and_b32_e32 v62, -8, v2
	v_add_u32_e32 v119, s6, v7
	v_add_u32_e32 v120, s7, v7
	v_add_u32_e32 v7, 0x440, v5
	v_add_u32_e32 v127, s6, v4
	v_add_u32_e32 v128, s7, v4
	v_mul_lo_u32 v4, v62, s0
	v_add_u32_e32 v113, s6, v5
	v_add_u32_e32 v114, s7, v5
	v_add_u32_e32 v121, s6, v7
	v_add_u32_e32 v122, s7, v7
	v_add_u32_e32 v7, 0x550, v5
	v_add_u32_e32 v5, 0x660, v5
	v_add_lshl_u32 v4, v4, v3, 1
	v_add_u32_e32 v125, s6, v5
	v_add_u32_e32 v126, s7, v5
	v_add_u32_e32 v5, 0x110, v4
	v_or_b32_e32 v2, 7, v2
	v_add_u32_e32 v131, s6, v5
	v_add_u32_e32 v132, s7, v5
	v_add_u32_e32 v5, 0x220, v4
	v_mul_lo_u32 v2, v2, s0
	v_add_u32_e32 v133, s6, v5
	v_add_u32_e32 v134, s7, v5
	v_add_u32_e32 v5, 0x330, v4
	v_add_lshl_u32 v2, v2, v3, 1
	v_add_u32_e32 v135, s6, v5
	v_add_u32_e32 v136, s7, v5
	v_add_u32_e32 v5, 0x440, v4
	v_add_u32_e32 v143, s6, v2
	v_add_u32_e32 v144, s7, v2
	v_mul_u32_u24_e32 v2, 0x88, v50
	v_add_u32_e32 v129, s6, v4
	v_add_u32_e32 v130, s7, v4
	v_add_u32_e32 v137, s6, v5
	v_add_u32_e32 v138, s7, v5
	v_add_u32_e32 v5, 0x550, v4
	v_add_u32_e32 v4, 0x660, v4
	v_lshlrev_b32_e32 v2, 1, v2
	v_ashrrev_i32_e32 v57, 31, v56
	v_ashrrev_i32_e32 v59, 31, v58
	v_ashrrev_i32_e32 v61, 31, v60
	v_add_u32_e32 v123, s6, v7
	v_add_u32_e32 v124, s7, v7
	v_ashrrev_i32_e32 v63, 31, v62
	v_add_u32_e32 v139, s6, v5
	v_add_u32_e32 v140, s7, v5
	v_add_u32_e32 v141, s6, v4
	v_add_u32_e32 v142, s7, v4
	v_add3_u32 v145, 0, v6, v2
	v_mov_b32_e32 v51, v0
	v_or_b32_e32 v64, 16, v50
	v_mov_b32_e32 v65, v0
	v_or_b32_e32 v66, 32, v50
	v_mov_b32_e32 v67, v0
	v_or_b32_e32 v68, 48, v50
	v_mov_b32_e32 v69, v0
	v_or_b32_e32 v70, 64, v50
	v_mov_b32_e32 v71, v0
	v_or_b32_e32 v72, 0x50, v50
	v_mov_b32_e32 v73, v0
	v_or_b32_e32 v74, 0x60, v50
	v_mov_b32_e32 v75, v0
	v_or_b32_e32 v76, 0x70, v50
	v_mov_b32_e32 v77, v0
	v_readlane_b32 s6, v254, 40
	s_mov_b32 s7, s2
	v_mbcnt_lo_u32_b32 v176, -1, 0
	v_mbcnt_hi_u32_b32 v176, -1, v176
	v_lshl_add_u32 v171, s33, 6, v176
	v_lshrrev_b32_e32 v172, 4, v171
	v_and_b32_e32 v173, 15, v171
	v_and_b32_e32 v174, 3, v172
	v_lshlrev_b32_e32 v174, 2, v174
	v_bfe_u32 v175, v172, 2, 2
	v_or_b32_e32 v174, v174, v175
	v_xor_b32_e32 v174, v173, v174
	v_lshlrev_b32_e32 v174, 4, v174
	v_lshl_add_u32 v168, v172, 8, v174
	v_add_u32_e32 v168, 0x11000, v168
	v_lshlrev_b32_e32 v166, 12, v172
	v_lshl_add_u32 v166, v173, 4, v166
	v_mov_b32_e32 v167, 0
	v_readlane_b32 s14, v254, 13
	v_readlane_b32 s15, v254, 14
	s_nop 0
	v_lshl_add_u64 v[166:167], s[14:15], 0, v[166:167]
	v_bfe_u32 v172, v176, 2, 2
	v_and_b32_e32 v173, 3, v176
	v_lshrrev_b32_e32 v174, 4, v176
	v_lshl_add_u32 v175, v174, 3, v172
	v_lshlrev_b32_e32 v177, 2, v172
	v_lshlrev_b32_e32 v174, 1, v174
	v_and_b32_e32 v178, 3, v174
	v_or_b32_e32 v178, v177, v178
	v_add_u32_e32 v174, 1, v174
	v_and_b32_e32 v174, 3, v174
	v_or_b32_e32 v174, v177, v174
	s_lshl_b32 s14, s33, 1
	v_lshrrev_b32_e32 v177, 1, v173
	v_add_u32_e32 v177, s14, v177
	v_and_b32_e32 v173, 1, v173
	v_lshlrev_b32_e32 v173, 3, v173
	v_xor_b32_e32 v178, v177, v178
	v_lshl_add_u32 v178, v178, 4, v173
	v_lshl_add_u32 v169, v175, 8, v178
	v_add_u32_e32 v169, 0x11000, v169
	v_xor_b32_e32 v174, v177, v174
	v_lshl_add_u32 v174, v174, 4, v173
	v_add_u32_e32 v175, 4, v175
	v_lshl_add_u32 v170, v175, 8, v174
	v_add_u32_e32 v170, 0x11000, v170
	v_and_b32_e32 v232, 15, v176
	v_mul_u32_u24_e32 v232, 0x110, v232
	v_lshrrev_b32_e32 v233, 4, v176
	v_lshl_add_u32 v232, v233, 3, v232
	s_lshl_b32 s14, s33, 5
	v_add_u32_e32 v232, s14, v232
	v_add_u32_e32 v232, 0x11000, v232
	v_lshrrev_b32_e32 v234, 4, v171
	v_and_b32_e32 v240, 15, v171
	v_lshlrev_b32_e32 v240, 4, v240
	v_mov_b32_e32 v241, 0
	v_mul_u32_u24_e32 v233, 0x110, v234
	v_add_u32_e32 v233, v233, v240
	v_add_u32_e32 v233, 0x11000, v233
; __device__ __forceinline__ unsigned cvt_pk_bf16(float lo, float hi) { const f2_t v = {lo, hi}; const bf2_t b = __builtin_convertvector(v, bf2_t); return __builtin_bit_cast(unsigned, b); }
; __device__ __forceinline__ f32x4 mfma16(bf16x8 a, bf16x8 b, f32x4 c) { return __builtin_amdgcn_mfma_f32_16x16x32_bf16(a, b, c, 0, 0, 0); }
; __device__ void fft2_phase(int wv, const Params& p, unsigned char* lds) {
;     ...
;     for (int unit = blockIdx.x; unit < 2048; unit += gridDim.x) {
;         const int gi = unit >> 3, cb = unit & 7;
;         const int seq = gi < 64 ? 0 : (gi < 128 ? 1 : 2); const int ka = gi - (seq == 0 ? 0 : (seq == 1 ? 64 : 128)); const int N1 = seq == 2 ? 128 : 64;
;         const size_t sbase = (size_t)seq * 8192;
; #pragma unroll
;         for (int ps = 0; ps < 4; ++ps) { const int idx = tid + ps * NTHR, b = idx & 127, c8 = (idx >> 7) * 8;
;             const bf16_t* rp = A1 + ((size_t)gi * 128 + b) * 2048 + cb * 128 + c8; const bf16x8 vr = *(const bf16x8*)rp, vi = *(const bf16x8*)(rp + 1024);
; #pragma unroll
;             for (int e = 0; e < 8; ++e) { XR[(c8 + e) * PW + b] = (bf16_t)vr[e]; XI[(c8 + e) * PW + b] = (bf16_t)vi[e]; } }
;         __syncthreads();
;         bf16x8 xr[4], xi[4], nxr[4];
; #pragma unroll
;         for (int kk = 0; kk < 4; ++kk) { xr[kk] = *(const bf16x8*)(XR + (16 * w + lr) * PW + 32 * kk + 8 * lq); xi[kk] = *(const bf16x8*)(XI + (16 * w + lr) * PW + 32 * kk + 8 * lq);
;             union { bf16x8 v; unsigned u[4]; } t; t.v = xr[kk]; t.u[0] ^= 0x80008000u; t.u[1] ^= 0x80008000u; t.u[2] ^= 0x80008000u; t.u[3] ^= 0x80008000u; nxr[kk] = t.v; }
; #pragma unroll
;         for (int i = 0; i < 8; ++i) { f32x4 re = {0, 0, 0, 0}, im = {0, 0, 0, 0};
; #pragma unroll
;             for (int kk = 0; kk < 4; ++kk) { const bf16x8 cf = *(const bf16x8*)(CT + (16 * i + lr) * PW + 32 * kk + 8 * lq), sf = *(const bf16x8*)(ST + (16 * i + lr) * PW + 32 * kk + 8 * lq);
;                 re = mfma16(xr[kk], cf, re); re = mfma16(xi[kk], sf, re); im = mfma16(xi[kk], cf, im); im = mfma16(nxr[kk], sf, im); }
;             const int kb = 16 * i + lr;
;             bf16_t* op = Y + (sbase + (size_t)N1 * kb + ka) * 2048 + cb * 128 + 16 * w + 4 * lq;
;             u32x2 o; o.x = cvt_pk_bf16(re[0], re[1]); o.y = cvt_pk_bf16(re[2], re[3]); *(u32x2*)op = o;
.LBB0_390:
	s_ashr_i32 s14, s7, 3
	s_cmpk_lt_i32 s14, 0x80
	s_cselect_b32 s0, 1, 2
	s_and_b32 s1, s7, 0xfffffe00
	s_cmpk_eq_i32 s1, 0x200
	s_movk_i32 s1, 0xff80
	s_cselect_b32 s1, 0xffffffc0, s1
	s_cmp_gt_i32 s14, 63
	s_cselect_b32 s10, s0, 0
	s_cselect_b32 s0, s1, 0
	s_ashr_i32 s15, s14, 31
	s_add_i32 s0, s0, s14
	s_lshl_b64 s[14:15], s[14:15], 19
	s_and_b32 s11, s6, 0x380
	v_lshl_add_u64 v[2:3], v[52:53], 0, s[14:15]
	s_lshl_b32 s36, s11, 1
	v_lshl_add_u64 v[2:3], v[2:3], 0, s[36:37]
	v_lshl_add_u64 v[162:163], v[166:167], 0, s[14:15]
	v_lshl_add_u64 v[162:163], v[162:163], 0, s[36:37]
	s_mov_b64 s[14:15], 0x20000
	global_load_dwordx4 v[180:183], v[162:163], off
	global_load_dwordx4 v[184:187], v[162:163], off offset:2048
	v_lshl_add_u64 v[162:163], v[162:163], 0, s[14:15]
	global_load_dwordx4 v[188:191], v[162:163], off
	global_load_dwordx4 v[192:195], v[162:163], off offset:2048
	v_lshl_add_u64 v[162:163], v[162:163], 0, s[14:15]
	global_load_dwordx4 v[196:199], v[162:163], off
	global_load_dwordx4 v[200:203], v[162:163], off offset:2048
	v_lshl_add_u64 v[162:163], v[162:163], 0, s[14:15]
	global_load_dwordx4 v[204:207], v[162:163], off
	global_load_dwordx4 v[208:211], v[162:163], off offset:2048
	s_lshl_b32 s1, s10, 13
	s_ashr_i32 s11, s0, 31
	s_add_u32 s0, s0, s1
	s_addc_u32 s1, s11, 0
	s_cmp_eq_u32 s10, 2
	s_cselect_b32 s10, 7, 6
	v_lshl_add_u64 v[78:79], v[54:55], 0, s[36:37]
	s_add_i32 s7, s7, s34
	s_add_i32 s6, s6, s92
	s_cmpk_lt_i32 s7, 0x800
	s_waitcnt vmcnt(7)
	ds_write_b128 v168, v[180:183] offset:0
	s_waitcnt vmcnt(6)
	ds_write_b128 v168, v[184:187] offset:32768
	s_waitcnt vmcnt(5)
	ds_write_b128 v168, v[188:191] offset:8192
	s_waitcnt vmcnt(4)
	ds_write_b128 v168, v[192:195] offset:40960
	s_waitcnt vmcnt(3)
	ds_write_b128 v168, v[196:199] offset:16384
	s_waitcnt vmcnt(2)
	ds_write_b128 v168, v[200:203] offset:49152
	s_waitcnt vmcnt(1)
	ds_write_b128 v168, v[204:207] offset:24576
	s_waitcnt vmcnt(0)
	ds_write_b128 v168, v[208:211] offset:57344
	s_waitcnt lgkmcnt(0)
	s_barrier
	ds_read_b64_tr_b16 v[46:47], v169 offset:0
	ds_read_b64_tr_b16 v[48:49], v170 offset:0
	ds_read_b64_tr_b16 v[38:39], v169 offset:32768
	ds_read_b64_tr_b16 v[40:41], v170 offset:32768
	ds_read_b64_tr_b16 v[34:35], v169 offset:8192
	ds_read_b64_tr_b16 v[36:37], v170 offset:8192
	ds_read_b64_tr_b16 v[30:31], v169 offset:40960
	ds_read_b64_tr_b16 v[32:33], v170 offset:40960
	ds_read_b64_tr_b16 v[22:23], v169 offset:16384
	ds_read_b64_tr_b16 v[24:25], v170 offset:16384
	ds_read_b64_tr_b16 v[14:15], v169 offset:49152
	ds_read_b64_tr_b16 v[16:17], v170 offset:49152
	s_waitcnt lgkmcnt(9)
	ds_read_b64_tr_b16 v[10:11], v169 offset:24576
	ds_read_b64_tr_b16 v[12:13], v170 offset:24576
	ds_read_b64_tr_b16 v[2:3], v169 offset:57344
	ds_read_b64_tr_b16 v[4:5], v170 offset:57344
	ds_read_b128 v[146:149], v145
	ds_read_b128 v[150:153], v145 offset:34816
	s_waitcnt lgkmcnt(13)
	v_xor_b32_e32 v42, 0x80008000, v46
	v_xor_b32_e32 v43, 0x80008000, v47
	v_xor_b32_e32 v44, 0x80008000, v48
	v_xor_b32_e32 v45, 0x80008000, v49
	s_waitcnt lgkmcnt(1)
	s_barrier
	v_mfma_f32_16x16x32_bf16 v[154:157], v[46:49], v[146:149], 0
	v_xor_b32_e32 v26, 0x80008000, v34
	v_xor_b32_e32 v27, 0x80008000, v35
	v_xor_b32_e32 v28, 0x80008000, v36
	v_mfma_f32_16x16x32_bf16 v[146:149], v[38:41], v[146:149], 0
	v_xor_b32_e32 v29, 0x80008000, v37
	v_xor_b32_e32 v18, 0x80008000, v22
	v_xor_b32_e32 v19, 0x80008000, v23
	s_waitcnt lgkmcnt(0)
	v_mfma_f32_16x16x32_bf16 v[154:157], v[38:41], v[150:153], v[154:157]
	v_xor_b32_e32 v20, 0x80008000, v24
	v_xor_b32_e32 v21, 0x80008000, v25
	v_xor_b32_e32 v6, 0x80008000, v10
	v_mfma_f32_16x16x32_bf16 v[146:149], v[42:45], v[150:153], v[146:149]
	ds_read_b128 v[150:153], v145 offset:64
	ds_read_b128 v[158:161], v145 offset:34880
	v_xor_b32_e32 v7, 0x80008000, v11
	v_xor_b32_e32 v8, 0x80008000, v12
	s_waitcnt lgkmcnt(1)
	v_mfma_f32_16x16x32_bf16 v[154:157], v[34:37], v[150:153], v[154:157]
	v_xor_b32_e32 v9, 0x80008000, v13
	v_mfma_f32_16x16x32_bf16 v[146:149], v[30:33], v[150:153], v[146:149]
	s_waitcnt lgkmcnt(0)
	v_mfma_f32_16x16x32_bf16 v[154:157], v[30:33], v[158:161], v[154:157]
	v_mfma_f32_16x16x32_bf16 v[146:149], v[26:29], v[158:161], v[146:149]
	ds_read_b128 v[150:153], v145 offset:128
	ds_read_b128 v[158:161], v145 offset:34944
	s_waitcnt lgkmcnt(1)
	v_mfma_f32_16x16x32_bf16 v[154:157], v[22:25], v[150:153], v[154:157]
	v_mfma_f32_16x16x32_bf16 v[146:149], v[14:17], v[150:153], v[146:149]
	s_waitcnt lgkmcnt(0)
	v_mfma_f32_16x16x32_bf16 v[154:157], v[14:17], v[158:161], v[154:157]
	v_mfma_f32_16x16x32_bf16 v[146:149], v[18:21], v[158:161], v[146:149]
	ds_read_b128 v[150:153], v145 offset:192
	ds_read_b128 v[158:161], v145 offset:35008
	s_waitcnt lgkmcnt(1)
	v_mfma_f32_16x16x32_bf16 v[154:157], v[10:13], v[150:153], v[154:157]
	v_mfma_f32_16x16x32_bf16 v[146:149], v[2:5], v[150:153], v[146:149]
	v_lshlrev_b64 v[150:151], s10, v[50:51]
	v_lshl_add_u64 v[150:151], s[0:1], 0, v[150:151]
	v_lshlrev_b64 v[150:151], 12, v[150:151]
	s_waitcnt lgkmcnt(0)
	v_mfma_f32_16x16x32_bf16 v[154:157], v[2:5], v[158:161], v[154:157]
	v_lshl_add_u64 v[150:151], v[78:79], 0, v[150:151]
	v_mfma_f32_16x16x32_bf16 v[146:149], v[6:9], v[158:161], v[146:149]
	s_nop 5
	v_cvt_pk_bf16_f32 v152, v154, v155
	v_cvt_pk_bf16_f32 v153, v156, v157
	v_cvt_pk_bf16_f32 v146, v146, v147
	v_cvt_pk_bf16_f32 v147, v148, v149
	ds_write_b64 v232, v[152:153] offset:0
	ds_write_b64 v232, v[146:147] offset:34816
	ds_read_b128 v[146:149], v145 offset:4352
	ds_read_b128 v[150:153], v145 offset:39168
	s_waitcnt lgkmcnt(1)
	v_mfma_f32_16x16x32_bf16 v[154:157], v[46:49], v[146:149], 0
	v_mfma_f32_16x16x32_bf16 v[146:149], v[38:41], v[146:149], 0
	s_waitcnt lgkmcnt(0)
; __device__ __forceinline__ unsigned cvt_pk_bf16(float lo, float hi) { const f2_t v = {lo, hi}; const bf2_t b = __builtin_convertvector(v, bf2_t); return __builtin_bit_cast(unsigned, b); }
; __device__ __forceinline__ f32x4 mfma16(bf16x8 a, bf16x8 b, f32x4 c) { return __builtin_amdgcn_mfma_f32_16x16x32_bf16(a, b, c, 0, 0, 0); }
; __device__ void fft2_phase(int wv, const Params& p, unsigned char* lds) {
;     ...
;         for (int i = 0; i < 8; ++i) { f32x4 re = {0, 0, 0, 0}, im = {0, 0, 0, 0};
; #pragma unroll
;             for (int kk = 0; kk < 4; ++kk) { const bf16x8 cf = *(const bf16x8*)(CT + (16 * i + lr) * PW + 32 * kk + 8 * lq), sf = *(const bf16x8*)(ST + (16 * i + lr) * PW + 32 * kk + 8 * lq);
;                 re = mfma16(xr[kk], cf, re); re = mfma16(xi[kk], sf, re); im = mfma16(xi[kk], cf, im); im = mfma16(nxr[kk], sf, im); }
;             const int kb = 16 * i + lr;
;             bf16_t* op = Y + (sbase + (size_t)N1 * kb + ka) * 2048 + cb * 128 + 16 * w + 4 * lq;
;             u32x2 o; o.x = cvt_pk_bf16(re[0], re[1]); o.y = cvt_pk_bf16(re[2], re[3]); *(u32x2*)op = o;
;             o.x = cvt_pk_bf16(im[0], im[1]); o.y = cvt_pk_bf16(im[2], im[3]); *(u32x2*)(op + 1024) = o; }
	v_mfma_f32_16x16x32_bf16 v[154:157], v[38:41], v[150:153], v[154:157]
	v_mfma_f32_16x16x32_bf16 v[146:149], v[42:45], v[150:153], v[146:149]
	ds_read_b128 v[150:153], v145 offset:4416
	ds_read_b128 v[158:161], v145 offset:39232
	s_waitcnt lgkmcnt(1)
	v_mfma_f32_16x16x32_bf16 v[154:157], v[34:37], v[150:153], v[154:157]
	v_mfma_f32_16x16x32_bf16 v[146:149], v[30:33], v[150:153], v[146:149]
	s_waitcnt lgkmcnt(0)
	v_mfma_f32_16x16x32_bf16 v[154:157], v[30:33], v[158:161], v[154:157]
	v_mfma_f32_16x16x32_bf16 v[146:149], v[26:29], v[158:161], v[146:149]
	ds_read_b128 v[150:153], v145 offset:4480
	ds_read_b128 v[158:161], v145 offset:39296
	s_waitcnt lgkmcnt(1)
	v_mfma_f32_16x16x32_bf16 v[154:157], v[22:25], v[150:153], v[154:157]
	v_mfma_f32_16x16x32_bf16 v[146:149], v[14:17], v[150:153], v[146:149]
	s_waitcnt lgkmcnt(0)
	v_mfma_f32_16x16x32_bf16 v[154:157], v[14:17], v[158:161], v[154:157]
	v_mfma_f32_16x16x32_bf16 v[146:149], v[18:21], v[158:161], v[146:149]
	ds_read_b128 v[150:153], v145 offset:4544
	ds_read_b128 v[158:161], v145 offset:39360
	s_waitcnt lgkmcnt(1)
	v_mfma_f32_16x16x32_bf16 v[154:157], v[10:13], v[150:153], v[154:157]
	v_mfma_f32_16x16x32_bf16 v[146:149], v[2:5], v[150:153], v[146:149]
	v_lshlrev_b64 v[150:151], s10, v[64:65]
	v_lshl_add_u64 v[150:151], s[0:1], 0, v[150:151]
	v_lshlrev_b64 v[150:151], 12, v[150:151]
	s_waitcnt lgkmcnt(0)
	v_mfma_f32_16x16x32_bf16 v[154:157], v[2:5], v[158:161], v[154:157]
	v_lshl_add_u64 v[150:151], v[78:79], 0, v[150:151]
	v_mfma_f32_16x16x32_bf16 v[146:149], v[6:9], v[158:161], v[146:149]
	s_nop 5
	v_cvt_pk_bf16_f32 v152, v154, v155
	v_cvt_pk_bf16_f32 v153, v156, v157
	v_cvt_pk_bf16_f32 v146, v146, v147
	v_cvt_pk_bf16_f32 v147, v148, v149
	ds_write_b64 v232, v[152:153] offset:4352
	ds_write_b64 v232, v[146:147] offset:39168
	ds_read_b128 v[146:149], v145 offset:8704
	ds_read_b128 v[150:153], v145 offset:43520
	s_waitcnt lgkmcnt(1)
	v_mfma_f32_16x16x32_bf16 v[154:157], v[46:49], v[146:149], 0
	v_mfma_f32_16x16x32_bf16 v[146:149], v[38:41], v[146:149], 0
	s_waitcnt lgkmcnt(0)
	v_mfma_f32_16x16x32_bf16 v[154:157], v[38:41], v[150:153], v[154:157]
	v_mfma_f32_16x16x32_bf16 v[146:149], v[42:45], v[150:153], v[146:149]
	ds_read_b128 v[150:153], v145 offset:8768
	ds_read_b128 v[158:161], v145 offset:43584
	s_waitcnt lgkmcnt(1)
	v_mfma_f32_16x16x32_bf16 v[154:157], v[34:37], v[150:153], v[154:157]
	v_mfma_f32_16x16x32_bf16 v[146:149], v[30:33], v[150:153], v[146:149]
	s_waitcnt lgkmcnt(0)
	v_mfma_f32_16x16x32_bf16 v[154:157], v[30:33], v[158:161], v[154:157]
	v_mfma_f32_16x16x32_bf16 v[146:149], v[26:29], v[158:161], v[146:149]
	ds_read_b128 v[150:153], v145 offset:8832
	ds_read_b128 v[158:161], v145 offset:43648
	s_waitcnt lgkmcnt(1)
	v_mfma_f32_16x16x32_bf16 v[154:157], v[22:25], v[150:153], v[154:157]
	v_mfma_f32_16x16x32_bf16 v[146:149], v[14:17], v[150:153], v[146:149]
	s_waitcnt lgkmcnt(0)
	v_mfma_f32_16x16x32_bf16 v[154:157], v[14:17], v[158:161], v[154:157]
	v_mfma_f32_16x16x32_bf16 v[146:149], v[18:21], v[158:161], v[146:149]
	ds_read_b128 v[150:153], v145 offset:8896
	ds_read_b128 v[158:161], v145 offset:43712
	s_waitcnt lgkmcnt(1)
	v_mfma_f32_16x16x32_bf16 v[154:157], v[10:13], v[150:153], v[154:157]
	v_mfma_f32_16x16x32_bf16 v[146:149], v[2:5], v[150:153], v[146:149]
	v_lshlrev_b64 v[150:151], s10, v[66:67]
	v_lshl_add_u64 v[150:151], s[0:1], 0, v[150:151]
	v_lshlrev_b64 v[150:151], 12, v[150:151]
	s_waitcnt lgkmcnt(0)
	v_mfma_f32_16x16x32_bf16 v[154:157], v[2:5], v[158:161], v[154:157]
	v_lshl_add_u64 v[150:151], v[78:79], 0, v[150:151]
	v_mfma_f32_16x16x32_bf16 v[146:149], v[6:9], v[158:161], v[146:149]
	s_nop 5
	v_cvt_pk_bf16_f32 v152, v154, v155
	v_cvt_pk_bf16_f32 v153, v156, v157
	v_cvt_pk_bf16_f32 v146, v146, v147
	v_cvt_pk_bf16_f32 v147, v148, v149
	ds_write_b64 v232, v[152:153] offset:8704
	ds_write_b64 v232, v[146:147] offset:43520
	ds_read_b128 v[146:149], v145 offset:13056
	ds_read_b128 v[150:153], v145 offset:47872
	s_waitcnt lgkmcnt(1)
	v_mfma_f32_16x16x32_bf16 v[154:157], v[46:49], v[146:149], 0
	v_mfma_f32_16x16x32_bf16 v[146:149], v[38:41], v[146:149], 0
	s_waitcnt lgkmcnt(0)
	v_mfma_f32_16x16x32_bf16 v[154:157], v[38:41], v[150:153], v[154:157]
	v_mfma_f32_16x16x32_bf16 v[146:149], v[42:45], v[150:153], v[146:149]
	ds_read_b128 v[150:153], v145 offset:13120
	ds_read_b128 v[158:161], v145 offset:47936
	s_waitcnt lgkmcnt(1)
	v_mfma_f32_16x16x32_bf16 v[154:157], v[34:37], v[150:153], v[154:157]
	v_mfma_f32_16x16x32_bf16 v[146:149], v[30:33], v[150:153], v[146:149]
	s_waitcnt lgkmcnt(0)
	v_mfma_f32_16x16x32_bf16 v[154:157], v[30:33], v[158:161], v[154:157]
	v_mfma_f32_16x16x32_bf16 v[146:149], v[26:29], v[158:161], v[146:149]
	ds_read_b128 v[150:153], v145 offset:13184
	ds_read_b128 v[158:161], v145 offset:48000
	s_waitcnt lgkmcnt(1)
	v_mfma_f32_16x16x32_bf16 v[154:157], v[22:25], v[150:153], v[154:157]
	v_mfma_f32_16x16x32_bf16 v[146:149], v[14:17], v[150:153], v[146:149]
	s_waitcnt lgkmcnt(0)
	v_mfma_f32_16x16x32_bf16 v[154:157], v[14:17], v[158:161], v[154:157]
	v_mfma_f32_16x16x32_bf16 v[146:149], v[18:21], v[158:161], v[146:149]
	ds_read_b128 v[150:153], v145 offset:13248
	ds_read_b128 v[158:161], v145 offset:48064
	s_waitcnt lgkmcnt(1)
	v_mfma_f32_16x16x32_bf16 v[154:157], v[10:13], v[150:153], v[154:157]
	v_mfma_f32_16x16x32_bf16 v[146:149], v[2:5], v[150:153], v[146:149]
	v_lshlrev_b64 v[150:151], s10, v[68:69]
	v_lshl_add_u64 v[150:151], s[0:1], 0, v[150:151]
	v_lshlrev_b64 v[150:151], 12, v[150:151]
	s_waitcnt lgkmcnt(0)
; __device__ __forceinline__ unsigned cvt_pk_bf16(float lo, float hi) { const f2_t v = {lo, hi}; const bf2_t b = __builtin_convertvector(v, bf2_t); return __builtin_bit_cast(unsigned, b); }
; __device__ __forceinline__ f32x4 mfma16(bf16x8 a, bf16x8 b, f32x4 c) { return __builtin_amdgcn_mfma_f32_16x16x32_bf16(a, b, c, 0, 0, 0); }
; __device__ void fft2_phase(int wv, const Params& p, unsigned char* lds) {
;     ...
;         for (int i = 0; i < 8; ++i) { f32x4 re = {0, 0, 0, 0}, im = {0, 0, 0, 0};
; #pragma unroll
;             for (int kk = 0; kk < 4; ++kk) { const bf16x8 cf = *(const bf16x8*)(CT + (16 * i + lr) * PW + 32 * kk + 8 * lq), sf = *(const bf16x8*)(ST + (16 * i + lr) * PW + 32 * kk + 8 * lq);
;                 re = mfma16(xr[kk], cf, re); re = mfma16(xi[kk], sf, re); im = mfma16(xi[kk], cf, im); im = mfma16(nxr[kk], sf, im); }
;             const int kb = 16 * i + lr;
;             bf16_t* op = Y + (sbase + (size_t)N1 * kb + ka) * 2048 + cb * 128 + 16 * w + 4 * lq;
;             u32x2 o; o.x = cvt_pk_bf16(re[0], re[1]); o.y = cvt_pk_bf16(re[2], re[3]); *(u32x2*)op = o;
;             o.x = cvt_pk_bf16(im[0], im[1]); o.y = cvt_pk_bf16(im[2], im[3]); *(u32x2*)(op + 1024) = o; }
	v_mfma_f32_16x16x32_bf16 v[154:157], v[2:5], v[158:161], v[154:157]
	v_lshl_add_u64 v[150:151], v[78:79], 0, v[150:151]
	v_mfma_f32_16x16x32_bf16 v[146:149], v[6:9], v[158:161], v[146:149]
	s_nop 5
	v_cvt_pk_bf16_f32 v152, v154, v155
	v_cvt_pk_bf16_f32 v153, v156, v157
	v_cvt_pk_bf16_f32 v146, v146, v147
	v_cvt_pk_bf16_f32 v147, v148, v149
	ds_write_b64 v232, v[152:153] offset:13056
	ds_write_b64 v232, v[146:147] offset:47872
	ds_read_b128 v[146:149], v145 offset:17408
	ds_read_b128 v[150:153], v145 offset:52224
	s_waitcnt lgkmcnt(1)
	v_mfma_f32_16x16x32_bf16 v[154:157], v[46:49], v[146:149], 0
	v_mfma_f32_16x16x32_bf16 v[146:149], v[38:41], v[146:149], 0
	s_waitcnt lgkmcnt(0)
	v_mfma_f32_16x16x32_bf16 v[154:157], v[38:41], v[150:153], v[154:157]
	v_mfma_f32_16x16x32_bf16 v[146:149], v[42:45], v[150:153], v[146:149]
	ds_read_b128 v[150:153], v145 offset:17472
	ds_read_b128 v[158:161], v145 offset:52288
	s_waitcnt lgkmcnt(1)
	v_mfma_f32_16x16x32_bf16 v[154:157], v[34:37], v[150:153], v[154:157]
	v_mfma_f32_16x16x32_bf16 v[146:149], v[30:33], v[150:153], v[146:149]
	s_waitcnt lgkmcnt(0)
	v_mfma_f32_16x16x32_bf16 v[154:157], v[30:33], v[158:161], v[154:157]
	v_mfma_f32_16x16x32_bf16 v[146:149], v[26:29], v[158:161], v[146:149]
	ds_read_b128 v[150:153], v145 offset:17536
	ds_read_b128 v[158:161], v145 offset:52352
	s_waitcnt lgkmcnt(1)
	v_mfma_f32_16x16x32_bf16 v[154:157], v[22:25], v[150:153], v[154:157]
	v_mfma_f32_16x16x32_bf16 v[146:149], v[14:17], v[150:153], v[146:149]
	s_waitcnt lgkmcnt(0)
	v_mfma_f32_16x16x32_bf16 v[154:157], v[14:17], v[158:161], v[154:157]
	v_mfma_f32_16x16x32_bf16 v[146:149], v[18:21], v[158:161], v[146:149]
	ds_read_b128 v[150:153], v145 offset:17600
	ds_read_b128 v[158:161], v145 offset:52416
	s_waitcnt lgkmcnt(1)
	v_mfma_f32_16x16x32_bf16 v[154:157], v[10:13], v[150:153], v[154:157]
	v_mfma_f32_16x16x32_bf16 v[146:149], v[2:5], v[150:153], v[146:149]
	v_lshlrev_b64 v[150:151], s10, v[70:71]
	v_lshl_add_u64 v[150:151], s[0:1], 0, v[150:151]
	v_lshlrev_b64 v[150:151], 12, v[150:151]
	s_waitcnt lgkmcnt(0)
	v_mfma_f32_16x16x32_bf16 v[154:157], v[2:5], v[158:161], v[154:157]
	v_lshl_add_u64 v[150:151], v[78:79], 0, v[150:151]
	v_mfma_f32_16x16x32_bf16 v[146:149], v[6:9], v[158:161], v[146:149]
	s_nop 5
	v_cvt_pk_bf16_f32 v152, v154, v155
	v_cvt_pk_bf16_f32 v153, v156, v157
	v_cvt_pk_bf16_f32 v146, v146, v147
	v_cvt_pk_bf16_f32 v147, v148, v149
	ds_write_b64 v232, v[152:153] offset:17408
	ds_write_b64 v232, v[146:147] offset:52224
	ds_read_b128 v[146:149], v145 offset:21760
	ds_read_b128 v[150:153], v145 offset:56576
	s_waitcnt lgkmcnt(1)
	v_mfma_f32_16x16x32_bf16 v[154:157], v[46:49], v[146:149], 0
	v_mfma_f32_16x16x32_bf16 v[146:149], v[38:41], v[146:149], 0
	s_waitcnt lgkmcnt(0)
	v_mfma_f32_16x16x32_bf16 v[154:157], v[38:41], v[150:153], v[154:157]
	v_mfma_f32_16x16x32_bf16 v[146:149], v[42:45], v[150:153], v[146:149]
	ds_read_b128 v[150:153], v145 offset:21824
	ds_read_b128 v[158:161], v145 offset:56640
	s_waitcnt lgkmcnt(1)
	v_mfma_f32_16x16x32_bf16 v[154:157], v[34:37], v[150:153], v[154:157]
	v_mfma_f32_16x16x32_bf16 v[146:149], v[30:33], v[150:153], v[146:149]
	s_waitcnt lgkmcnt(0)
	v_mfma_f32_16x16x32_bf16 v[154:157], v[30:33], v[158:161], v[154:157]
	v_mfma_f32_16x16x32_bf16 v[146:149], v[26:29], v[158:161], v[146:149]
	ds_read_b128 v[150:153], v145 offset:21888
	ds_read_b128 v[158:161], v145 offset:56704
	s_waitcnt lgkmcnt(1)
	v_mfma_f32_16x16x32_bf16 v[154:157], v[22:25], v[150:153], v[154:157]
	v_mfma_f32_16x16x32_bf16 v[146:149], v[14:17], v[150:153], v[146:149]
	s_waitcnt lgkmcnt(0)
	v_mfma_f32_16x16x32_bf16 v[154:157], v[14:17], v[158:161], v[154:157]
	v_mfma_f32_16x16x32_bf16 v[146:149], v[18:21], v[158:161], v[146:149]
	ds_read_b128 v[150:153], v145 offset:21952
	ds_read_b128 v[158:161], v145 offset:56768
	s_waitcnt lgkmcnt(1)
	v_mfma_f32_16x16x32_bf16 v[154:157], v[10:13], v[150:153], v[154:157]
	v_mfma_f32_16x16x32_bf16 v[146:149], v[2:5], v[150:153], v[146:149]
	v_lshlrev_b64 v[150:151], s10, v[72:73]
	v_lshl_add_u64 v[150:151], s[0:1], 0, v[150:151]
	v_lshlrev_b64 v[150:151], 12, v[150:151]
	s_waitcnt lgkmcnt(0)
	v_mfma_f32_16x16x32_bf16 v[154:157], v[2:5], v[158:161], v[154:157]
	v_lshl_add_u64 v[150:151], v[78:79], 0, v[150:151]
	v_mfma_f32_16x16x32_bf16 v[146:149], v[6:9], v[158:161], v[146:149]
	s_nop 5
	v_cvt_pk_bf16_f32 v152, v154, v155
	v_cvt_pk_bf16_f32 v153, v156, v157
	v_cvt_pk_bf16_f32 v146, v146, v147
	v_cvt_pk_bf16_f32 v147, v148, v149
	ds_write_b64 v232, v[152:153] offset:21760
	ds_write_b64 v232, v[146:147] offset:56576
	ds_read_b128 v[146:149], v145 offset:26112
	ds_read_b128 v[150:153], v145 offset:60928
	s_waitcnt lgkmcnt(1)
	v_mfma_f32_16x16x32_bf16 v[154:157], v[46:49], v[146:149], 0
	v_mfma_f32_16x16x32_bf16 v[146:149], v[38:41], v[146:149], 0
	s_waitcnt lgkmcnt(0)
	v_mfma_f32_16x16x32_bf16 v[154:157], v[38:41], v[150:153], v[154:157]
	v_mfma_f32_16x16x32_bf16 v[146:149], v[42:45], v[150:153], v[146:149]
	ds_read_b128 v[150:153], v145 offset:26176
	ds_read_b128 v[158:161], v145 offset:60992
	s_waitcnt lgkmcnt(1)
	v_mfma_f32_16x16x32_bf16 v[154:157], v[34:37], v[150:153], v[154:157]
	v_mfma_f32_16x16x32_bf16 v[146:149], v[30:33], v[150:153], v[146:149]
	s_waitcnt lgkmcnt(0)
; __device__ __forceinline__ unsigned cvt_pk_bf16(float lo, float hi) { const f2_t v = {lo, hi}; const bf2_t b = __builtin_convertvector(v, bf2_t); return __builtin_bit_cast(unsigned, b); }
; __device__ __forceinline__ f32x4 mfma16(bf16x8 a, bf16x8 b, f32x4 c) { return __builtin_amdgcn_mfma_f32_16x16x32_bf16(a, b, c, 0, 0, 0); }
; __device__ void fft2_phase(int wv, const Params& p, unsigned char* lds) {
;     ...
;         for (int i = 0; i < 8; ++i) { f32x4 re = {0, 0, 0, 0}, im = {0, 0, 0, 0};
; #pragma unroll
;             for (int kk = 0; kk < 4; ++kk) { const bf16x8 cf = *(const bf16x8*)(CT + (16 * i + lr) * PW + 32 * kk + 8 * lq), sf = *(const bf16x8*)(ST + (16 * i + lr) * PW + 32 * kk + 8 * lq);
;                 re = mfma16(xr[kk], cf, re); re = mfma16(xi[kk], sf, re); im = mfma16(xi[kk], cf, im); im = mfma16(nxr[kk], sf, im); }
;             const int kb = 16 * i + lr;
;             bf16_t* op = Y + (sbase + (size_t)N1 * kb + ka) * 2048 + cb * 128 + 16 * w + 4 * lq;
;             u32x2 o; o.x = cvt_pk_bf16(re[0], re[1]); o.y = cvt_pk_bf16(re[2], re[3]); *(u32x2*)op = o;
;             o.x = cvt_pk_bf16(im[0], im[1]); o.y = cvt_pk_bf16(im[2], im[3]); *(u32x2*)(op + 1024) = o; }
;         __syncthreads();
;     }
	v_mfma_f32_16x16x32_bf16 v[154:157], v[30:33], v[158:161], v[154:157]
	v_mfma_f32_16x16x32_bf16 v[146:149], v[26:29], v[158:161], v[146:149]
	ds_read_b128 v[150:153], v145 offset:26240
	ds_read_b128 v[158:161], v145 offset:61056
	s_waitcnt lgkmcnt(1)
	v_mfma_f32_16x16x32_bf16 v[154:157], v[22:25], v[150:153], v[154:157]
	v_mfma_f32_16x16x32_bf16 v[146:149], v[14:17], v[150:153], v[146:149]
	s_waitcnt lgkmcnt(0)
	v_mfma_f32_16x16x32_bf16 v[154:157], v[14:17], v[158:161], v[154:157]
	v_mfma_f32_16x16x32_bf16 v[146:149], v[18:21], v[158:161], v[146:149]
	ds_read_b128 v[150:153], v145 offset:26304
	ds_read_b128 v[158:161], v145 offset:61120
	s_waitcnt lgkmcnt(1)
	v_mfma_f32_16x16x32_bf16 v[154:157], v[10:13], v[150:153], v[154:157]
	v_mfma_f32_16x16x32_bf16 v[146:149], v[2:5], v[150:153], v[146:149]
	v_lshlrev_b64 v[150:151], s10, v[74:75]
	v_lshl_add_u64 v[150:151], s[0:1], 0, v[150:151]
	v_lshlrev_b64 v[150:151], 12, v[150:151]
	s_waitcnt lgkmcnt(0)
	v_mfma_f32_16x16x32_bf16 v[154:157], v[2:5], v[158:161], v[154:157]
	v_lshl_add_u64 v[150:151], v[78:79], 0, v[150:151]
	v_mfma_f32_16x16x32_bf16 v[146:149], v[6:9], v[158:161], v[146:149]
	s_nop 5
	v_cvt_pk_bf16_f32 v152, v154, v155
	v_cvt_pk_bf16_f32 v153, v156, v157
	v_cvt_pk_bf16_f32 v146, v146, v147
	v_cvt_pk_bf16_f32 v147, v148, v149
	ds_write_b64 v232, v[152:153] offset:26112
	ds_write_b64 v232, v[146:147] offset:60928
	ds_read_b128 v[146:149], v145 offset:30464
	ds_read_b128 v[150:153], v145 offset:65280
	s_waitcnt lgkmcnt(1)
	v_mfma_f32_16x16x32_bf16 v[46:49], v[46:49], v[146:149], 0
	s_waitcnt lgkmcnt(0)
	v_mfma_f32_16x16x32_bf16 v[46:49], v[38:41], v[150:153], v[46:49]
	v_mfma_f32_16x16x32_bf16 v[38:41], v[38:41], v[146:149], 0
	v_mfma_f32_16x16x32_bf16 v[38:41], v[42:45], v[150:153], v[38:41]
	ds_read_b128 v[42:45], v145 offset:30528
	ds_read_b128 v[146:149], v145 offset:65344
	s_waitcnt lgkmcnt(1)
	v_mfma_f32_16x16x32_bf16 v[34:37], v[34:37], v[42:45], v[46:49]
	s_waitcnt lgkmcnt(0)
	v_mfma_f32_16x16x32_bf16 v[34:37], v[30:33], v[146:149], v[34:37]
	v_mfma_f32_16x16x32_bf16 v[30:33], v[30:33], v[42:45], v[38:41]
	v_mfma_f32_16x16x32_bf16 v[26:29], v[26:29], v[146:149], v[30:33]
	s_nop 6
	ds_read_b128 v[30:33], v145 offset:30592
	ds_read_b128 v[38:41], v145 offset:65408
	s_waitcnt lgkmcnt(1)
	v_mfma_f32_16x16x32_bf16 v[22:25], v[22:25], v[30:33], v[34:37]
	s_waitcnt lgkmcnt(0)
	v_mfma_f32_16x16x32_bf16 v[22:25], v[14:17], v[38:41], v[22:25]
	v_mfma_f32_16x16x32_bf16 v[14:17], v[14:17], v[30:33], v[26:29]
	v_mfma_f32_16x16x32_bf16 v[14:17], v[18:21], v[38:41], v[14:17]
	ds_read_b128 v[18:21], v145 offset:30656
	s_nop 0
	ds_read_b128 v[26:29], v145 offset:65472
	s_waitcnt lgkmcnt(1)
	v_mfma_f32_16x16x32_bf16 v[10:13], v[10:13], v[18:21], v[22:25]
	s_waitcnt lgkmcnt(0)
	v_mfma_f32_16x16x32_bf16 v[10:13], v[2:5], v[26:29], v[10:13]
	v_mfma_f32_16x16x32_bf16 v[2:5], v[2:5], v[18:21], v[14:17]
	v_mfma_f32_16x16x32_bf16 v[2:5], v[6:9], v[26:29], v[2:5]
	v_lshlrev_b64 v[6:7], s10, v[76:77]
	v_lshl_add_u64 v[6:7], s[0:1], 0, v[6:7]
	v_lshlrev_b64 v[6:7], 12, v[6:7]
	v_lshl_add_u64 v[6:7], v[78:79], 0, v[6:7]
	s_nop 1
	v_cvt_pk_bf16_f32 v8, v10, v11
	v_cvt_pk_bf16_f32 v9, v12, v13
	v_cvt_pk_bf16_f32 v2, v2, v3
	v_cvt_pk_bf16_f32 v3, v4, v5
	ds_write_b64 v232, v[8:9] offset:30464
	ds_write_b64 v232, v[2:3] offset:65280
	s_waitcnt lgkmcnt(0)
	s_barrier
	ds_read_b128 v[180:183], v233 offset:0
	ds_read_b128 v[184:187], v233 offset:34816
	ds_read_b128 v[188:191], v233 offset:8704
	ds_read_b128 v[192:195], v233 offset:43520
	ds_read_b128 v[196:199], v233 offset:17408
	ds_read_b128 v[200:203], v233 offset:52224
	ds_read_b128 v[204:207], v233 offset:26112
	ds_read_b128 v[208:211], v233 offset:60928
	v_lshl_add_u64 v[238:239], s[76:77], 0, v[240:241]
	v_lshl_add_u64 v[238:239], v[238:239], 0, s[36:37]
	v_add_u32_e32 v236, 0, v234
	v_lshlrev_b32_e32 v236, s10, v236
	v_mov_b32_e32 v237, 0
	v_lshl_add_u64 v[236:237], v[236:237], 0, s[0:1]
	v_lshlrev_b64 v[236:237], 12, v[236:237]
	v_lshl_add_u64 v[236:237], v[238:239], 0, v[236:237]
	s_waitcnt lgkmcnt(7)
	global_store_dwordx4 v[236:237], v[180:183], off
	s_waitcnt lgkmcnt(6)
	global_store_dwordx4 v[236:237], v[184:187], off offset:2048
	v_add_u32_e32 v236, 32, v234
	v_lshlrev_b32_e32 v236, s10, v236
	v_mov_b32_e32 v237, 0
	v_lshl_add_u64 v[236:237], v[236:237], 0, s[0:1]
	v_lshlrev_b64 v[236:237], 12, v[236:237]
	v_lshl_add_u64 v[236:237], v[238:239], 0, v[236:237]
	s_waitcnt lgkmcnt(5)
	global_store_dwordx4 v[236:237], v[188:191], off
	s_waitcnt lgkmcnt(4)
	global_store_dwordx4 v[236:237], v[192:195], off offset:2048
	v_add_u32_e32 v236, 64, v234
	v_lshlrev_b32_e32 v236, s10, v236
	v_mov_b32_e32 v237, 0
	v_lshl_add_u64 v[236:237], v[236:237], 0, s[0:1]
	v_lshlrev_b64 v[236:237], 12, v[236:237]
	v_lshl_add_u64 v[236:237], v[238:239], 0, v[236:237]
	s_waitcnt lgkmcnt(3)
	global_store_dwordx4 v[236:237], v[196:199], off
	s_waitcnt lgkmcnt(2)
	global_store_dwordx4 v[236:237], v[200:203], off offset:2048
	v_add_u32_e32 v236, 96, v234
	v_lshlrev_b32_e32 v236, s10, v236
	v_mov_b32_e32 v237, 0
	v_lshl_add_u64 v[236:237], v[236:237], 0, s[0:1]
	v_lshlrev_b64 v[236:237], 12, v[236:237]
	v_lshl_add_u64 v[236:237], v[238:239], 0, v[236:237]
	s_waitcnt lgkmcnt(1)
	global_store_dwordx4 v[236:237], v[204:207], off
	s_waitcnt lgkmcnt(0)
	global_store_dwordx4 v[236:237], v[208:211], off offset:2048
	s_barrier
	s_cmpk_lt_i32 s7, 0x800
	s_cbranch_scc1 .LBB0_390
